# loop-edge edit: unit-order division by group size (always 8) replaced by shift/mask in the gate/up GEMM unit header
# speedup vs baseline: 1.0039x; 1.0039x over previous
;     __host__ __device__ bool next(int i, Unit& u) const {
;         const long L = (long)i * G + c; if (L >= nwg) return false;
;         int wgid = (int)L; { const int q = nwg / NXCD, r = nwg % NXCD, xcd = wgid % NXCD, off = wgid / NXCD; wgid = (xcd < r ? xcd * (q + 1) : r * (q + 1) + (xcd - r) * q) + off; }
;         const int nig = WGM * nN, gid = wgid / nig, fm = gid * WGM, gsz = (nM - fm) < WGM ? (nM - fm) : WGM;
;         u.pm = fm + ((wgid % nig) % gsz); u.pn = (wgid % nig) / gsz; return true;
;     }
.LBB0_125:
	s_add_i32 s69, s69, 1
	s_mul_i32 s6, s69, s85
	s_mul_hi_u32 s7, s69, s62
	s_add_i32 s7, s7, s6
	s_mul_i32 s6, s69, s62
	s_add_u32 s28, s6, s83
	s_addc_u32 s29, s7, s91
	v_mov_b64_e32 v[6:7], 0xb00
	v_cmp_lt_i64_e64 s[6:7], s[28:29], v[6:7]
	v_mov_b64_e32 v[6:7], 0xaff
	v_cmp_gt_i64_e32 vcc, s[28:29], v[6:7]
	s_cbranch_vccnz .LBB0_127
	s_ashr_i32 s24, s28, 31
	s_lshr_b32 s24, s24, 29
	s_add_i32 s24, s28, s24
	s_ashr_i32 s25, s24, 3
	s_and_b32 s24, s24, -8
	s_sub_i32 s24, s28, s24
	s_cmp_lt_i32 s24, 0
	s_movk_i32 s26, 0x161
	s_cselect_b32 s26, s26, 0x160
	s_mul_i32 s24, s24, s26
	s_add_i32 s24, s24, s25
	s_mul_hi_i32 s25, s24, 0x2e8ba2e9
	s_lshr_b32 s26, s25, 31
	s_ashr_i32 s25, s25, 6
	s_add_i32 s25, s25, s26
	s_lshl_b32 s26, s25, 3
	s_sub_i32 s27, 64, s26
	s_min_i32 s27, s27, 8
	s_mulk_i32 s25, 0x160
	s_sub_i32 s25, s24, s25
	s_ashr_i32 s24, s25, 3
	s_and_b32 s25, s25, 7
	s_add_i32 s26, s26, s25

;     __host__ __device__ bool next(int i, Unit& u) const {
;         const long L = (long)i * G + c; if (L >= nwg) return false;
;         int wgid = (int)L; { const int q = nwg / NXCD, r = nwg % NXCD, xcd = wgid % NXCD, off = wgid / NXCD; wgid = (xcd < r ? xcd * (q + 1) : r * (q + 1) + (xcd - r) * q) + off; }
;         const int nig = WGM * nN, gid = wgid / nig, fm = gid * WGM, gsz = (nM - fm) < WGM ? (nM - fm) : WGM;
;         u.pm = fm + ((wgid % nig) % gsz); u.pn = (wgid % nig) / gsz; return true;
;     }
.LBB0_1013:
	s_add_i32 s47, s47, 1
	s_mul_i32 s6, s47, s85
	s_mul_hi_u32 s7, s47, s62
	s_add_i32 s7, s7, s6
	s_mul_i32 s6, s47, s62
	s_add_u32 s18, s6, s83
	s_addc_u32 s19, s7, s91
	v_mov_b64_e32 v[6:7], 0x600
	v_cmp_lt_i64_e64 s[6:7], s[18:19], v[6:7]
	v_mov_b64_e32 v[6:7], 0x5ff
	v_cmp_gt_i64_e32 vcc, s[18:19], v[6:7]
	s_cbranch_vccnz .LBB0_1015
	s_ashr_i32 s14, s18, 31
	s_lshr_b32 s14, s14, 29
	s_add_i32 s14, s18, s14
	s_ashr_i32 s15, s14, 3
	s_and_b32 s14, s14, -8
	s_sub_i32 s14, s18, s14
	s_cmp_lt_i32 s14, 0
	s_movk_i32 s16, 0xc1
	s_cselect_b32 s16, s16, 0xc0
	s_mul_i32 s14, s14, s16
	s_add_i32 s14, s14, s15
	s_mul_hi_i32 s15, s14, 0x2aaaaaab
	s_lshr_b32 s16, s15, 31
	s_ashr_i32 s15, s15, 5
	s_add_i32 s15, s15, s16
	s_lshl_b32 s16, s15, 3
	s_sub_i32 s17, 64, s16
	s_min_i32 s17, s17, 8
	s_mulk_i32 s15, 0xc0
	s_sub_i32 s15, s14, s15
	s_ashr_i32 s14, s15, 3
	s_and_b32 s15, s15, 7
	s_add_i32 s16, s16, s15
